# v76 with the P0 plain weight conversion as per-wave 64x64 pieces transposed through LDS: 16-byte stores covering complete 128-byte destination row segments
# speedup vs baseline: 1.0107x; 1.0107x over previous
.Lwf_plain:
	s_load_dword s6, s[0:1], 0x4c8
	v_and_b32_e32 v29, 63, v155
	v_lshrrev_b32_e32 v24, 6, v155
	v_lshlrev_b32_e32 v26, 2, v29
	v_mul_u32_u24_e32 v27, 0x90, v29
	v_readfirstlane_b32 s58, v24
	v_bfe_u32 v28, v155, 3, 3
	v_and_b32_e32 v29, 7, v155
	s_waitcnt lgkmcnt(0)
	s_cmpk_lg_u32 s6, 0x100
	s_cbranch_scc1 .Lwf_generic
	s_mul_i32 s7, s58, 0x2400
	s_add_i32 s7, s7, 0xa000
	v_add_u32_e32 v27, s7, v27
	v_mul_u32_u24_e32 v24, 0x90, v28
	v_add_u32_e32 v24, s7, v24
	v_lshl_add_u32 v24, v29, 4, v24
	s_lshl_b32 s59, s92, 3
	s_add_i32 s58, s59, s58
	s_mov_b32 s6, 0
.Lwf_loop:
	s_lshl_b32 s7, s6, 11
	s_add_i32 s7, s7, s58
	s_and_b32 s8, s7, 1
	s_lshr_b32 s7, s7, 1
	s_addk_i32 s7, 0x100
	s_mov_b32 s30, 2
	s_cmpk_ge_i32 s7, 0x300
	s_cselect_b32 s30, 3, s30
	s_cmpk_ge_i32 s7, 0x500
	s_cselect_b32 s30, 4, s30
	s_cmpk_ge_i32 s7, 0x700
	s_cselect_b32 s30, 5, s30
	s_cmpk_ge_i32 s7, 0x900
	s_cselect_b32 s30, 6, s30
	s_cmpk_ge_i32 s7, 0xb00
	s_cselect_b32 s30, 7, s30
	s_cmpk_ge_i32 s7, 0xd00
	s_cselect_b32 s30, 8, s30
	s_cmpk_ge_i32 s7, 0xf00
	s_cselect_b32 s30, 9, s30
	s_cmpk_ge_i32 s7, 0x1100
	s_cselect_b32 s30, 10, s30
	s_cmpk_ge_i32 s7, 0x1280
	s_cselect_b32 s30, 11, s30
	s_cmpk_ge_i32 s7, 0x1400
	s_cselect_b32 s30, 12, s30
	s_cmpk_ge_i32 s7, 0x1480
	s_cselect_b32 s30, 13, s30
	s_mul_i32 s59, s30, 48
	s_add_u32 s10, s0, s59
	s_addc_u32 s11, s1, 0
	s_load_dwordx2 s[50:51], s[10:11], 0x100
	s_load_dwordx2 s[52:53], s[10:11], 0x110
	s_load_dwordx2 s[90:91], s[10:11], 0x118
	s_load_dword s30, s[10:11], 0x128
	s_load_dwordx2 vcc, s[0:1], 0xf8
	s_waitcnt lgkmcnt(0)
	s_sub_i32 s7, s7, s30
	s_lshr_b32 s59, s90, 7
	s_add_i32 s10, s59, -1
	s_and_b32 s10, s7, s10
	s_ff1_i32_b32 s59, s59
	s_lshr_b32 s7, s7, s59
	s_lshl_b32 s10, s10, 7
	s_lshl_b32 s8, s8, 6
	s_add_i32 s10, s10, s8
	s_lshl_b32 s11, s7, 6
	s_mul_i32 s59, s10, s91
	s_add_i32 s59, s59, s11
	s_lshl_b32 s59, s59, 2
	s_add_u32 s50, s50, s59
	s_addc_u32 s51, s51, 0
	s_mul_i32 s59, s11, s90
	s_add_i32 s59, s59, s10
	s_lshl_b32 s59, s59, 1
	s_add_u32 s52, s52, s59
	s_addc_u32 s53, s53, 0
	s_add_u32 s52, s52, vcc_lo
	s_addc_u32 s53, s53, vcc_hi
	s_lshl_b32 s54, s90, 1
	v_mul_lo_u32 v85, v28, s54
	v_lshl_add_u32 v85, v29, 4, v85
	s_lshl_b32 s54, s54, 3
	s_mov_b32 s55, 0
	s_lshl_b32 s91, s91, 2
	global_load_dword v0, v26, s[50:51] nt
	s_add_u32 s50, s50, s91
	s_addc_u32 s51, s51, 0
	global_load_dword v1, v26, s[50:51] nt
	s_add_u32 s50, s50, s91
	s_addc_u32 s51, s51, 0
	global_load_dword v2, v26, s[50:51] nt
	s_add_u32 s50, s50, s91
	s_addc_u32 s51, s51, 0
	global_load_dword v3, v26, s[50:51] nt
	s_add_u32 s50, s50, s91
	s_addc_u32 s51, s51, 0
	global_load_dword v4, v26, s[50:51] nt
	s_add_u32 s50, s50, s91
	s_addc_u32 s51, s51, 0
	global_load_dword v5, v26, s[50:51] nt
	s_add_u32 s50, s50, s91
	s_addc_u32 s51, s51, 0
	global_load_dword v6, v26, s[50:51] nt
	s_add_u32 s50, s50, s91
	s_addc_u32 s51, s51, 0
	global_load_dword v7, v26, s[50:51] nt
	s_add_u32 s50, s50, s91
	s_addc_u32 s51, s51, 0
	global_load_dword v8, v26, s[50:51] nt
	s_add_u32 s50, s50, s91
	s_addc_u32 s51, s51, 0
	global_load_dword v9, v26, s[50:51] nt
	s_add_u32 s50, s50, s91
	s_addc_u32 s51, s51, 0
	global_load_dword v10, v26, s[50:51] nt
	s_add_u32 s50, s50, s91
	s_addc_u32 s51, s51, 0
	global_load_dword v11, v26, s[50:51] nt
	s_add_u32 s50, s50, s91
	s_addc_u32 s51, s51, 0
	global_load_dword v12, v26, s[50:51] nt
	s_add_u32 s50, s50, s91
	s_addc_u32 s51, s51, 0
	global_load_dword v13, v26, s[50:51] nt
	s_add_u32 s50, s50, s91
	s_addc_u32 s51, s51, 0
	global_load_dword v14, v26, s[50:51] nt
	s_add_u32 s50, s50, s91
	s_addc_u32 s51, s51, 0
	global_load_dword v15, v26, s[50:51] nt
	s_add_u32 s50, s50, s91
	s_addc_u32 s51, s51, 0
	global_load_dword v30, v26, s[50:51] nt
	s_add_u32 s50, s50, s91
	s_addc_u32 s51, s51, 0
	global_load_dword v31, v26, s[50:51] nt
	s_add_u32 s50, s50, s91
	s_addc_u32 s51, s51, 0
	global_load_dword v32, v26, s[50:51] nt
	s_add_u32 s50, s50, s91
	s_addc_u32 s51, s51, 0
	global_load_dword v33, v26, s[50:51] nt
	s_add_u32 s50, s50, s91
	s_addc_u32 s51, s51, 0
	global_load_dword v34, v26, s[50:51] nt
	s_add_u32 s50, s50, s91
	s_addc_u32 s51, s51, 0
	global_load_dword v35, v26, s[50:51] nt
	s_add_u32 s50, s50, s91
	s_addc_u32 s51, s51, 0
	global_load_dword v36, v26, s[50:51] nt
	s_add_u32 s50, s50, s91
	s_addc_u32 s51, s51, 0
	global_load_dword v37, v26, s[50:51] nt
	s_add_u32 s50, s50, s91
	s_addc_u32 s51, s51, 0
	global_load_dword v38, v26, s[50:51] nt
	s_add_u32 s50, s50, s91
	s_addc_u32 s51, s51, 0
	global_load_dword v39, v26, s[50:51] nt
	s_add_u32 s50, s50, s91
	s_addc_u32 s51, s51, 0
	global_load_dword v40, v26, s[50:51] nt
	s_add_u32 s50, s50, s91
	s_addc_u32 s51, s51, 0
	global_load_dword v41, v26, s[50:51] nt
	s_add_u32 s50, s50, s91
	s_addc_u32 s51, s51, 0
	global_load_dword v42, v26, s[50:51] nt
	s_add_u32 s50, s50, s91
	s_addc_u32 s51, s51, 0
	global_load_dword v43, v26, s[50:51] nt
	s_add_u32 s50, s50, s91
	s_addc_u32 s51, s51, 0
	global_load_dword v44, v26, s[50:51] nt
	s_add_u32 s50, s50, s91
	s_addc_u32 s51, s51, 0
	global_load_dword v45, v26, s[50:51] nt
	s_add_u32 s50, s50, s91
	s_addc_u32 s51, s51, 0
	global_load_dword v46, v26, s[50:51] nt
	s_add_u32 s50, s50, s91
	s_addc_u32 s51, s51, 0
	global_load_dword v47, v26, s[50:51] nt
	s_add_u32 s50, s50, s91
	s_addc_u32 s51, s51, 0
	global_load_dword v48, v26, s[50:51] nt
	s_add_u32 s50, s50, s91
	s_addc_u32 s51, s51, 0
	global_load_dword v49, v26, s[50:51] nt
	s_add_u32 s50, s50, s91
	s_addc_u32 s51, s51, 0
	global_load_dword v50, v26, s[50:51] nt
	s_add_u32 s50, s50, s91
	s_addc_u32 s51, s51, 0
	global_load_dword v51, v26, s[50:51] nt
	s_add_u32 s50, s50, s91
	s_addc_u32 s51, s51, 0
	global_load_dword v52, v26, s[50:51] nt
	s_add_u32 s50, s50, s91
	s_addc_u32 s51, s51, 0
	global_load_dword v53, v26, s[50:51] nt
	s_add_u32 s50, s50, s91
	s_addc_u32 s51, s51, 0
	global_load_dword v54, v26, s[50:51] nt
	s_add_u32 s50, s50, s91
	s_addc_u32 s51, s51, 0
	global_load_dword v55, v26, s[50:51] nt
	s_add_u32 s50, s50, s91
	s_addc_u32 s51, s51, 0
	global_load_dword v56, v26, s[50:51] nt
	s_add_u32 s50, s50, s91
	s_addc_u32 s51, s51, 0
	global_load_dword v57, v26, s[50:51] nt
	s_add_u32 s50, s50, s91
	s_addc_u32 s51, s51, 0
	global_load_dword v58, v26, s[50:51] nt
	s_add_u32 s50, s50, s91
	s_addc_u32 s51, s51, 0
	global_load_dword v59, v26, s[50:51] nt
	s_add_u32 s50, s50, s91
	s_addc_u32 s51, s51, 0
	global_load_dword v60, v26, s[50:51] nt
	s_add_u32 s50, s50, s91
	s_addc_u32 s51, s51, 0
	global_load_dword v61, v26, s[50:51] nt
	s_add_u32 s50, s50, s91
	s_addc_u32 s51, s51, 0
	global_load_dword v62, v26, s[50:51] nt
	s_add_u32 s50, s50, s91
	s_addc_u32 s51, s51, 0
	global_load_dword v63, v26, s[50:51] nt
	s_add_u32 s50, s50, s91
	s_addc_u32 s51, s51, 0
	global_load_dword v64, v26, s[50:51] nt
	s_add_u32 s50, s50, s91
	s_addc_u32 s51, s51, 0
	global_load_dword v65, v26, s[50:51] nt
	s_add_u32 s50, s50, s91
	s_addc_u32 s51, s51, 0
	global_load_dword v66, v26, s[50:51] nt
	s_add_u32 s50, s50, s91
	s_addc_u32 s51, s51, 0
	global_load_dword v67, v26, s[50:51] nt
	s_add_u32 s50, s50, s91
	s_addc_u32 s51, s51, 0
	global_load_dword v68, v26, s[50:51] nt
	s_add_u32 s50, s50, s91
	s_addc_u32 s51, s51, 0
	global_load_dword v69, v26, s[50:51] nt
	s_add_u32 s50, s50, s91
	s_addc_u32 s51, s51, 0
	global_load_dword v70, v26, s[50:51] nt
	s_add_u32 s50, s50, s91
	s_addc_u32 s51, s51, 0
	global_load_dword v71, v26, s[50:51] nt
	s_add_u32 s50, s50, s91
	s_addc_u32 s51, s51, 0
	global_load_dword v72, v26, s[50:51] nt
	s_add_u32 s50, s50, s91
	s_addc_u32 s51, s51, 0
	global_load_dword v73, v26, s[50:51] nt
	s_add_u32 s50, s50, s91
	s_addc_u32 s51, s51, 0
	global_load_dword v74, v26, s[50:51] nt
	s_add_u32 s50, s50, s91
	s_addc_u32 s51, s51, 0
	global_load_dword v75, v26, s[50:51] nt
	s_add_u32 s50, s50, s91
	s_addc_u32 s51, s51, 0
	global_load_dword v76, v26, s[50:51] nt
	s_add_u32 s50, s50, s91
	s_addc_u32 s51, s51, 0
	global_load_dword v77, v26, s[50:51] nt
	s_waitcnt vmcnt(48)
	v_cvt_pk_bf16_f32 v78, v0, v1
	ds_write_b32 v27, v78 offset:0
	v_cvt_pk_bf16_f32 v79, v2, v3
	ds_write_b32 v27, v79 offset:4
	v_cvt_pk_bf16_f32 v80, v4, v5
	ds_write_b32 v27, v80 offset:8
	v_cvt_pk_bf16_f32 v81, v6, v7
	ds_write_b32 v27, v81 offset:12
	v_cvt_pk_bf16_f32 v82, v8, v9
	ds_write_b32 v27, v82 offset:16
	v_cvt_pk_bf16_f32 v83, v10, v11
	ds_write_b32 v27, v83 offset:20
	v_cvt_pk_bf16_f32 v78, v12, v13
	ds_write_b32 v27, v78 offset:24
	v_cvt_pk_bf16_f32 v79, v14, v15
	ds_write_b32 v27, v79 offset:28
	s_waitcnt vmcnt(32)
	v_cvt_pk_bf16_f32 v78, v30, v31
	ds_write_b32 v27, v78 offset:32
	v_cvt_pk_bf16_f32 v79, v32, v33
	ds_write_b32 v27, v79 offset:36
	v_cvt_pk_bf16_f32 v80, v34, v35
	ds_write_b32 v27, v80 offset:40
	v_cvt_pk_bf16_f32 v81, v36, v37
	ds_write_b32 v27, v81 offset:44
	v_cvt_pk_bf16_f32 v82, v38, v39
	ds_write_b32 v27, v82 offset:48
	v_cvt_pk_bf16_f32 v83, v40, v41
	ds_write_b32 v27, v83 offset:52
	v_cvt_pk_bf16_f32 v78, v42, v43
	ds_write_b32 v27, v78 offset:56
	v_cvt_pk_bf16_f32 v79, v44, v45
	ds_write_b32 v27, v79 offset:60
	s_waitcnt vmcnt(16)
	v_cvt_pk_bf16_f32 v78, v46, v47
	ds_write_b32 v27, v78 offset:64
	v_cvt_pk_bf16_f32 v79, v48, v49
	ds_write_b32 v27, v79 offset:68
	v_cvt_pk_bf16_f32 v80, v50, v51
	ds_write_b32 v27, v80 offset:72
	v_cvt_pk_bf16_f32 v81, v52, v53
	ds_write_b32 v27, v81 offset:76
	v_cvt_pk_bf16_f32 v82, v54, v55
	ds_write_b32 v27, v82 offset:80
	v_cvt_pk_bf16_f32 v83, v56, v57
	ds_write_b32 v27, v83 offset:84
	v_cvt_pk_bf16_f32 v78, v58, v59
	ds_write_b32 v27, v78 offset:88
	v_cvt_pk_bf16_f32 v79, v60, v61
	ds_write_b32 v27, v79 offset:92
	s_waitcnt vmcnt(0)
	v_cvt_pk_bf16_f32 v78, v62, v63
	ds_write_b32 v27, v78 offset:96
	v_cvt_pk_bf16_f32 v79, v64, v65
	ds_write_b32 v27, v79 offset:100
	v_cvt_pk_bf16_f32 v80, v66, v67
	ds_write_b32 v27, v80 offset:104
	v_cvt_pk_bf16_f32 v81, v68, v69
	ds_write_b32 v27, v81 offset:108
	v_cvt_pk_bf16_f32 v82, v70, v71
	ds_write_b32 v27, v82 offset:112
	v_cvt_pk_bf16_f32 v83, v72, v73
	ds_write_b32 v27, v83 offset:116
	v_cvt_pk_bf16_f32 v78, v74, v75
	ds_write_b32 v27, v78 offset:120
	v_cvt_pk_bf16_f32 v79, v76, v77
	ds_write_b32 v27, v79 offset:124
	s_waitcnt lgkmcnt(0)
	ds_read_b128 v[86:89], v24 offset:0
	ds_read_b128 v[90:93], v24 offset:1152
	ds_read_b128 v[94:97], v24 offset:2304
	ds_read_b128 v[98:101], v24 offset:3456
	s_waitcnt lgkmcnt(3)
	global_store_dwordx4 v85, v[86:89], s[52:53]
	s_add_u32 s52, s52, s54
	s_addc_u32 s53, s53, s55
	s_waitcnt lgkmcnt(2)
	global_store_dwordx4 v85, v[90:93], s[52:53]
	s_add_u32 s52, s52, s54
	s_addc_u32 s53, s53, s55
	s_waitcnt lgkmcnt(1)
	global_store_dwordx4 v85, v[94:97], s[52:53]
	s_add_u32 s52, s52, s54
	s_addc_u32 s53, s53, s55
	s_waitcnt lgkmcnt(0)
	global_store_dwordx4 v85, v[98:101], s[52:53]
	s_add_u32 s52, s52, s54
	s_addc_u32 s53, s53, s55
	s_nop 4
	ds_read_b128 v[86:89], v24 offset:4608
	ds_read_b128 v[90:93], v24 offset:5760
	ds_read_b128 v[94:97], v24 offset:6912
	ds_read_b128 v[98:101], v24 offset:8064
	s_waitcnt lgkmcnt(3)
	global_store_dwordx4 v85, v[86:89], s[52:53]
	s_add_u32 s52, s52, s54
	s_addc_u32 s53, s53, s55
	s_waitcnt lgkmcnt(2)
	global_store_dwordx4 v85, v[90:93], s[52:53]
	s_add_u32 s52, s52, s54
	s_addc_u32 s53, s53, s55
	s_waitcnt lgkmcnt(1)
	global_store_dwordx4 v85, v[94:97], s[52:53]
	s_add_u32 s52, s52, s54
	s_addc_u32 s53, s53, s55
	s_waitcnt lgkmcnt(0)
	global_store_dwordx4 v85, v[98:101], s[52:53]
	s_add_u32 s52, s52, s54
	s_addc_u32 s53, s53, s55
	s_add_i32 s6, s6, 1
	s_cmp_lt_u32 s6, 5
	s_cbranch_scc1 .Lwf_loop
	s_cmp_ge_u32 s92, 0x80
	s_movk_i32 s7, 0x1700
	s_cselect_b32 s89, 0x1600, s7
	s_add_i32 s89, s89, s92
	s_cmp_ge_i32 s89, s62
	s_cbranch_scc1 .LBB0_113
